# GU unit loops: next-unit index computation and pointer setup moved into the MFMA gaps of the first K pair (on v10)
# speedup vs baseline: 1.0021x; 1.0021x over previous
;     __device__ __forceinline__ bool unit(int L, Unit& u) const { u.g = L; return order_mn(L, T / 256, NGU / 256, u.pm, u.pn); }
;     __device__ __forceinline__ bool unit(int L, Unit& u) const { u.g = L; return order_mn(L, T / 256, D / 256, u.pm, u.pn); }
;     __device__ __forceinline__ bool unit(int L, Unit& u) const { u.g = 0; return order_mn(L, T / 256, 8, u.pm, u.pn); }
;     __device__ __forceinline__ bool unit(int L, Unit& u) const { if (L >= NG * 4) return false; u.g = L >> 2; u.pm = (L >> 1) & 1; u.pn = L & 1; return true; }
;     __device__ __forceinline__ bool unit(int L, Unit& u) const { if (L >= NG * 8) return false; u.g = L >> 3; u.pm = (L >> 2) & 1; u.pn = L & 3; return true; }
; __device__ __forceinline__ bool order_mn(int L, int nM, int nN, int& pm, int& pn) {
;     const int nwg = nM * nN; if (L >= nwg) return false;
;     int wgid = L; { const int q = nwg / 8, r = nwg % 8, xcd = wgid % 8, off = wgid / 8; wgid = (xcd < r ? xcd * (q + 1) : r * (q + 1) + (xcd - r) * q) + off; }
;     const int nig = 8 * nN, gid = wgid / nig, fm = gid * 8, gsz = (nM - fm) < 8 ? (nM - fm) : 8;
;     pm = fm + ((wgid % nig) % gsz); pn = (wgid % nig) / gsz; return true;
; }
;     ...
;         const bool has_next = p.unit((ui + 1) * G + c, nxt);
;         const char* nA = has_next ? p.a0(nxt) : cA; const char* nB = has_next ? p.b0(nxt) : cB;
;         const char* nA2 = P::SEG ? (has_next ? p.a1(nxt) : cA2) : nA; const char* nB2 = P::SEG ? (has_next ? p.b1(nxt) : cB2) : nB;
.LBB0_229:
.LBB0_231:
	ds_read_b128 v[0:3], v152
	ds_read_b128 v[4:7], v152 offset:1024
	ds_read_b128 v[8:11], v152 offset:2048
	ds_read_b128 v[12:15], v152 offset:3072
	s_add_u32 s34, s26, 0x40080
	s_addc_u32 s35, s27, 0
	s_mov_b32 m0, s47
	v_lshl_add_u64 v[48:49], s[34:35], 0, v[136:137]
	ds_read_b128 v[16:19], v153
	ds_read_b128 v[20:23], v153 offset:1024
	ds_read_b128 v[24:27], v153 offset:2048
	ds_read_b128 v[28:31], v153 offset:3072
	ds_read_b128 v[32:35], v153 offset:4096
	ds_read_b128 v[36:39], v153 offset:5120
	ds_read_b128 v[40:43], v153 offset:6144
	ds_read_b128 v[44:47], v153 offset:7168
	global_load_lds_dwordx4 v[48:49], off
	s_mov_b32 m0, s48
	v_lshl_add_u64 v[48:49], s[34:35], 0, v[132:133]
	global_load_lds_dwordx4 v[48:49], off
	s_waitcnt lgkmcnt(8)
	s_barrier
	s_waitcnt lgkmcnt(0)
	v_mfma_f32_16x16x32_bf16 v[48:51], v[0:3], v[16:19], 0
	s_add_i32 s46, s46, 1
	v_mfma_f32_16x16x32_bf16 v[52:55], v[8:11], v[16:19], 0
	s_mul_i32 s17, s46, s96
	v_mfma_f32_16x16x32_bf16 v[56:59], v[0:3], v[24:27], 0
	s_add_i32 s17, s17, s33
	v_mfma_f32_16x16x32_bf16 v[60:63], v[8:11], v[24:27], 0
	s_cmpk_lt_i32 s17, 0xb00
	v_mfma_f32_16x16x32_bf16 v[64:67], v[0:3], v[32:35], 0
	s_cselect_b64 s[30:31], -1, 0
	v_mfma_f32_16x16x32_bf16 v[68:71], v[8:11], v[32:35], 0
	s_cmpk_gt_i32 s17, 0xaff
	v_mfma_f32_16x16x32_bf16 v[72:75], v[0:3], v[40:43], 0
	s_cselect_b64 s[14:15], -1, 0
	v_mfma_f32_16x16x32_bf16 v[76:79], v[8:11], v[40:43], 0
	s_ashr_i32 s16, s17, 31
	v_mfma_f32_16x16x32_bf16 v[48:51], v[4:7], v[20:23], v[48:51]
	s_lshr_b32 s16, s16, 29
	v_mfma_f32_16x16x32_bf16 v[52:55], v[12:15], v[20:23], v[52:55]
	s_add_i32 s16, s17, s16
	v_mfma_f32_16x16x32_bf16 v[56:59], v[4:7], v[28:31], v[56:59]
	s_ashr_i32 s18, s16, 3
	v_mfma_f32_16x16x32_bf16 v[60:63], v[12:15], v[28:31], v[60:63]
	s_and_b32 s16, s16, -8
	v_mfma_f32_16x16x32_bf16 v[64:67], v[4:7], v[36:39], v[64:67]
	s_sub_i32 s16, s17, s16
	v_mfma_f32_16x16x32_bf16 v[68:71], v[12:15], v[36:39], v[68:71]
	s_lshr_b32 s17, s16, 31
	v_mfma_f32_16x16x32_bf16 v[72:75], v[4:7], v[44:47], v[72:75]
	s_or_b32 s17, s17, 0x160
	v_mfma_f32_16x16x32_bf16 v[76:79], v[12:15], v[44:47], v[76:79]
	s_barrier
	v_lshl_add_u64 v[218:219], s[28:29], 0, v[134:135]
	s_mov_b32 m0, s49
	v_lshl_add_u64 v[96:97], v[218:219], 0, s[8:9]
	v_lshl_add_u64 v[238:239], s[28:29], 0, v[130:131]
	ds_read_b128 v[80:83], v154
	ds_read_b128 v[84:87], v154 offset:1024
	ds_read_b128 v[88:91], v154 offset:2048
	ds_read_b128 v[92:95], v154 offset:3072
	global_load_lds_dwordx4 v[96:97], off
	s_mov_b32 m0, s50
	v_lshl_add_u64 v[96:97], v[238:239], 0, s[8:9]
	global_load_lds_dwordx4 v[96:97], off
	s_barrier
	s_waitcnt lgkmcnt(0)
	v_mfma_f32_16x16x32_bf16 v[96:99], v[80:83], v[16:19], 0
	s_mul_i32 s16, s17, s16
	v_mfma_f32_16x16x32_bf16 v[16:19], v[88:91], v[16:19], 0
	s_add_i32 s16, s16, s18
	v_mfma_f32_16x16x32_bf16 v[100:103], v[80:83], v[24:27], 0
	s_mul_hi_i32 s17, s16, 0x2e8ba2e9
	v_mfma_f32_16x16x32_bf16 v[24:27], v[88:91], v[24:27], 0
	s_lshr_b32 s18, s17, 31
	v_mfma_f32_16x16x32_bf16 v[104:107], v[80:83], v[32:35], 0
	s_ashr_i32 s17, s17, 5
	v_mfma_f32_16x16x32_bf16 v[32:35], v[88:91], v[32:35], 0
	s_add_i32 s17, s17, s18
	v_mfma_f32_16x16x32_bf16 v[108:111], v[80:83], v[40:43], 0
	s_lshl_b32 s18, s17, 3
	v_mfma_f32_16x16x32_bf16 v[40:43], v[88:91], v[40:43], 0
	s_sub_i32 s19, 0x80, s18
	v_mfma_f32_16x16x32_bf16 v[116:119], v[84:87], v[20:23], v[96:99]
	s_min_u32 s19, s19, 8
	v_mfma_f32_16x16x32_bf16 v[16:19], v[92:95], v[20:23], v[16:19]
	s_mulk_i32 s17, 0xb0
	v_mfma_f32_16x16x32_bf16 v[20:23], v[84:87], v[28:31], v[100:103]
	s_sub_i32 s20, s16, s17
	v_mfma_f32_16x16x32_bf16 v[24:27], v[92:95], v[28:31], v[24:27]
	v_cvt_f32_ubyte0_e32 v251, s19
	v_mfma_f32_16x16x32_bf16 v[28:31], v[84:87], v[36:39], v[104:107]
	v_cvt_f32_i32_e32 v250, s20
	v_mfma_f32_16x16x32_bf16 v[32:35], v[92:95], v[36:39], v[32:35]
	v_rcp_iflag_f32_e32 v252, v251
	v_mfma_f32_16x16x32_bf16 v[36:39], v[84:87], v[44:47], v[108:111]
	s_ashr_i32 s16, s20, 30
	v_mfma_f32_16x16x32_bf16 v[40:43], v[92:95], v[44:47], v[40:43]
	v_lshl_add_u64 v[246:247], s[26:27], 0, v[136:137]
	s_mov_b32 m0, s25
	v_lshl_add_u64 v[142:143], v[246:247], 0, s[8:9]
	v_lshl_add_u64 v[248:249], s[26:27], 0, v[132:133]
	s_barrier
	ds_read_b128 v[44:47], v153 offset:16384
	ds_read_b128 v[96:99], v153 offset:17408
	ds_read_b128 v[100:103], v153 offset:18432
	ds_read_b128 v[104:107], v153 offset:19456
	ds_read_b128 v[108:111], v153 offset:20480
	ds_read_b128 v[112:115], v153 offset:21504
	ds_read_b128 v[120:123], v153 offset:22528
	ds_read_b128 v[124:127], v153 offset:23552
	global_load_lds_dwordx4 v[142:143], off
	s_mov_b32 m0, s41
	v_lshl_add_u64 v[142:143], v[248:249], 0, s[8:9]
	global_load_lds_dwordx4 v[142:143], off
	s_barrier
	s_waitcnt lgkmcnt(0)
	v_mfma_f32_16x16x32_bf16 v[142:145], v[0:3], v[44:47], 0
	s_or_b32 s21, s16, 1
	v_mfma_f32_16x16x32_bf16 v[158:161], v[8:11], v[44:47], 0
	v_mul_f32_e32 v252, v250, v252
	v_mfma_f32_16x16x32_bf16 v[162:165], v[0:3], v[100:103], 0
	v_trunc_f32_e32 v252, v252
	v_mfma_f32_16x16x32_bf16 v[166:169], v[8:11], v[100:103], 0
	v_fma_f32 v250, -v252, v251, v250
	v_mfma_f32_16x16x32_bf16 v[170:173], v[0:3], v[108:111], 0
	v_cvt_i32_f32_e32 v252, v252
	v_mfma_f32_16x16x32_bf16 v[174:177], v[8:11], v[108:111], 0
	v_cmp_ge_f32_e64 s[16:17], |v250|, v251
	v_mfma_f32_16x16x32_bf16 v[0:3], v[0:3], v[120:123], 0
	s_and_b64 s[16:17], s[16:17], exec
	v_mfma_f32_16x16x32_bf16 v[8:11], v[8:11], v[120:123], 0
	s_cselect_b32 s16, s21, 0
	v_mfma_f32_16x16x32_bf16 v[142:145], v[4:7], v[96:99], v[142:145]
	v_readfirstlane_b32 s17, v252
	v_mfma_f32_16x16x32_bf16 v[162:165], v[4:7], v[104:107], v[162:165]
	s_add_i32 s17, s17, s16
	v_mfma_f32_16x16x32_bf16 v[170:173], v[4:7], v[112:115], v[170:173]
	s_sext_i32_i16 s16, s17
	v_mfma_f32_16x16x32_bf16 v[0:3], v[4:7], v[124:127], v[0:3]
	s_mul_i32 s17, s17, s19
	v_mfma_f32_16x16x32_bf16 v[4:7], v[12:15], v[124:127], v[8:11]
	s_sub_i32 s17, s20, s17
	v_mfma_f32_16x16x32_bf16 v[158:161], v[12:15], v[96:99], v[158:161]
	s_sext_i32_i16 s17, s17
	v_mfma_f32_16x16x32_bf16 v[166:169], v[12:15], v[104:107], v[166:169]
	s_add_i32 s18, s18, s17
	v_mfma_f32_16x16x32_bf16 v[174:177], v[12:15], v[112:115], v[174:177]
	s_barrier
;     __device__ __forceinline__ bool unit(int L, Unit& u) const { u.g = L; return order_mn(L, T / 256, NGU / 256, u.pm, u.pn); }
;     __device__ __forceinline__ bool unit(int L, Unit& u) const { u.g = L; return order_mn(L, T / 256, D / 256, u.pm, u.pn); }
;     __device__ __forceinline__ bool unit(int L, Unit& u) const { u.g = 0; return order_mn(L, T / 256, 8, u.pm, u.pn); }
;     __device__ __forceinline__ bool unit(int L, Unit& u) const { if (L >= NG * 4) return false; u.g = L >> 2; u.pm = (L >> 1) & 1; u.pn = L & 1; return true; }
;     __device__ __forceinline__ bool unit(int L, Unit& u) const { if (L >= NG * 8) return false; u.g = L >> 3; u.pm = (L >> 2) & 1; u.pn = L & 3; return true; }
;     ...
;         const bool has_next = p.unit((ui + 1) * G + c, nxt);
;         const char* nA = has_next ? p.a0(nxt) : cA; const char* nB = has_next ? p.b0(nxt) : cB;
;         const char* nA2 = P::SEG ? (has_next ? p.a1(nxt) : cA2) : nA; const char* nB2 = P::SEG ? (has_next ? p.b1(nxt) : cB2) : nB;
	s_add_u32 s34, s28, 0x40100
	s_addc_u32 s35, s29, 0
	s_mov_b32 m0, s55
	v_lshl_add_u64 v[8:9], s[34:35], 0, v[134:135]
	global_load_lds_dwordx4 v[8:9], off
	s_mov_b32 m0, s56
	v_lshl_add_u64 v[8:9], s[34:35], 0, v[130:131]
	global_load_lds_dwordx4 v[8:9], off
	s_waitcnt vmcnt(6)
	s_barrier
	v_mfma_f32_16x16x32_bf16 v[8:11], v[80:83], v[44:47], 0
	s_ashr_i32 s19, s18, 31
	v_mfma_f32_16x16x32_bf16 v[12:15], v[88:91], v[44:47], 0
	s_lshl_b64 s[20:21], s[18:19], 19
	v_mfma_f32_16x16x32_bf16 v[44:47], v[80:83], v[100:103], 0
	s_add_u32 s20, s10, s20
	v_mfma_f32_16x16x32_bf16 v[100:103], v[88:91], v[100:103], 0
	s_addc_u32 s21, s11, s21
	v_mfma_f32_16x16x32_bf16 v[178:181], v[80:83], v[108:111], 0
	s_ashr_i32 s17, s16, 31
	v_mfma_f32_16x16x32_bf16 v[108:111], v[88:91], v[108:111], 0
	s_lshl_b64 s[22:23], s[16:17], 19
	v_mfma_f32_16x16x32_bf16 v[80:83], v[80:83], v[120:123], 0
	s_add_u32 s22, s39, s22
	v_mfma_f32_16x16x32_bf16 v[88:91], v[88:91], v[120:123], 0
	s_addc_u32 s23, s40, s23
	v_mfma_f32_16x16x32_bf16 v[12:15], v[92:95], v[96:99], v[12:15]
	v_mfma_f32_16x16x32_bf16 v[44:47], v[84:87], v[104:107], v[44:47]
	v_mfma_f32_16x16x32_bf16 v[182:185], v[84:87], v[96:99], v[8:11]
	v_mfma_f32_16x16x32_bf16 v[186:189], v[92:95], v[104:107], v[100:103]
	v_mfma_f32_16x16x32_bf16 v[178:181], v[84:87], v[112:115], v[178:181]
	v_mfma_f32_16x16x32_bf16 v[190:193], v[92:95], v[112:115], v[108:111]
	v_mfma_f32_16x16x32_bf16 v[194:197], v[84:87], v[124:127], v[80:83]
	v_mfma_f32_16x16x32_bf16 v[198:201], v[92:95], v[124:127], v[88:91]
	s_barrier
	ds_read_b128 v[8:11], v155
	ds_read_b128 v[202:205], v155 offset:1024
	ds_read_b128 v[206:209], v155 offset:2048
	ds_read_b128 v[210:213], v155 offset:3072
	s_add_u32 s34, s26, 0x40100
	s_addc_u32 s35, s27, 0
	s_mov_b32 m0, s42
	v_lshl_add_u64 v[80:81], s[34:35], 0, v[136:137]
	ds_read_b128 v[84:87], v153 offset:32768
	ds_read_b128 v[92:95], v153 offset:33792
	ds_read_b128 v[100:103], v153 offset:34816
	ds_read_b128 v[214:217], v153 offset:35840
	ds_read_b128 v[108:111], v153 offset:36864
	ds_read_b128 v[222:225], v153 offset:37888
	ds_read_b128 v[124:127], v153 offset:38912
	ds_read_b128 v[226:229], v153 offset:39936
	global_load_lds_dwordx4 v[80:81], off
	s_mov_b32 m0, s43
	v_lshl_add_u64 v[80:81], s[34:35], 0, v[132:133]
	global_load_lds_dwordx4 v[80:81], off
	s_waitcnt lgkmcnt(8)
	s_barrier
	s_waitcnt lgkmcnt(0)
	v_mfma_f32_16x16x32_bf16 v[48:51], v[8:11], v[84:87], v[48:51]
	v_mfma_f32_16x16x32_bf16 v[52:55], v[206:209], v[84:87], v[52:55]
	v_mfma_f32_16x16x32_bf16 v[56:59], v[8:11], v[100:103], v[56:59]
	v_mfma_f32_16x16x32_bf16 v[60:63], v[206:209], v[100:103], v[60:63]
	v_mfma_f32_16x16x32_bf16 v[64:67], v[8:11], v[108:111], v[64:67]
	v_mfma_f32_16x16x32_bf16 v[68:71], v[206:209], v[108:111], v[68:71]
	v_mfma_f32_16x16x32_bf16 v[72:75], v[8:11], v[124:127], v[72:75]
	v_mfma_f32_16x16x32_bf16 v[76:79], v[206:209], v[124:127], v[76:79]
	v_mfma_f32_16x16x32_bf16 v[120:123], v[202:205], v[92:95], v[48:51]
	v_mfma_f32_16x16x32_bf16 v[112:115], v[210:213], v[92:95], v[52:55]
	v_mfma_f32_16x16x32_bf16 v[104:107], v[202:205], v[214:217], v[56:59]
	v_mfma_f32_16x16x32_bf16 v[96:99], v[210:213], v[214:217], v[60:63]
	v_mfma_f32_16x16x32_bf16 v[88:91], v[202:205], v[222:225], v[64:67]
	v_mfma_f32_16x16x32_bf16 v[80:83], v[210:213], v[222:225], v[68:71]
	v_mfma_f32_16x16x32_bf16 v[72:75], v[202:205], v[226:229], v[72:75]
	v_mfma_f32_16x16x32_bf16 v[60:63], v[210:213], v[226:229], v[76:79]
	s_barrier
	s_mov_b32 m0, s57
	v_lshl_add_u64 v[48:49], v[218:219], 0, s[12:13]
	ds_read_b128 v[52:55], v156
	ds_read_b128 v[230:233], v156 offset:1024
	ds_read_b128 v[68:71], v156 offset:2048
	ds_read_b128 v[234:237], v156 offset:3072
	global_load_lds_dwordx4 v[48:49], off
	s_mov_b32 m0, s58
	v_lshl_add_u64 v[48:49], v[238:239], 0, s[12:13]
	global_load_lds_dwordx4 v[48:49], off
	s_barrier
;     ...
;         G_PAIR(0, 1);
; #pragma unroll 1
;         for (int t = 2; t < nt; t += 2) G_PAIR(t, 0);
	s_waitcnt lgkmcnt(0)
	v_mfma_f32_16x16x32_bf16 v[48:51], v[52:55], v[84:87], v[116:119]
	v_mfma_f32_16x16x32_bf16 v[16:19], v[68:71], v[84:87], v[16:19]
	v_mfma_f32_16x16x32_bf16 v[20:23], v[52:55], v[100:103], v[20:23]
	v_mfma_f32_16x16x32_bf16 v[24:27], v[68:71], v[100:103], v[24:27]
	v_mfma_f32_16x16x32_bf16 v[28:31], v[52:55], v[108:111], v[28:31]
	v_mfma_f32_16x16x32_bf16 v[32:35], v[68:71], v[108:111], v[32:35]
	v_mfma_f32_16x16x32_bf16 v[36:39], v[52:55], v[124:127], v[36:39]
	v_mfma_f32_16x16x32_bf16 v[40:43], v[68:71], v[124:127], v[40:43]
	v_mfma_f32_16x16x32_bf16 v[124:127], v[230:233], v[92:95], v[48:51]
	v_mfma_f32_16x16x32_bf16 v[116:119], v[234:237], v[92:95], v[16:19]
	v_mfma_f32_16x16x32_bf16 v[108:111], v[230:233], v[214:217], v[20:23]
	v_mfma_f32_16x16x32_bf16 v[100:103], v[234:237], v[214:217], v[24:27]
	v_mfma_f32_16x16x32_bf16 v[92:95], v[230:233], v[222:225], v[28:31]
	v_mfma_f32_16x16x32_bf16 v[84:87], v[234:237], v[222:225], v[32:35]
	v_mfma_f32_16x16x32_bf16 v[76:79], v[230:233], v[226:229], v[36:39]
	v_mfma_f32_16x16x32_bf16 v[64:67], v[234:237], v[226:229], v[40:43]
	s_mov_b32 m0, s44
	v_lshl_add_u64 v[16:17], v[246:247], 0, s[12:13]
	s_barrier
	ds_read_b128 v[20:23], v153 offset:49152
	ds_read_b128 v[28:31], v153 offset:50176
	ds_read_b128 v[36:39], v153 offset:51200
	ds_read_b128 v[214:217], v153 offset:52224
	ds_read_b128 v[222:225], v153 offset:53248
	ds_read_b128 v[226:229], v153 offset:54272
	ds_read_b128 v[238:241], v153 offset:55296
	ds_read_b128 v[242:245], v153 offset:56320
	global_load_lds_dwordx4 v[16:17], off
	s_mov_b32 m0, s45
	v_lshl_add_u64 v[16:17], v[248:249], 0, s[12:13]
	global_load_lds_dwordx4 v[16:17], off
	s_barrier
	s_waitcnt lgkmcnt(0)
	v_mfma_f32_16x16x32_bf16 v[16:19], v[8:11], v[20:23], v[142:145]
	v_mfma_f32_16x16x32_bf16 v[24:27], v[206:209], v[20:23], v[158:161]
	v_mfma_f32_16x16x32_bf16 v[32:35], v[8:11], v[36:39], v[162:165]
	v_mfma_f32_16x16x32_bf16 v[142:145], v[206:209], v[36:39], v[166:169]
	v_mfma_f32_16x16x32_bf16 v[158:161], v[8:11], v[222:225], v[170:173]
	v_mfma_f32_16x16x32_bf16 v[162:165], v[206:209], v[222:225], v[174:177]
	v_mfma_f32_16x16x32_bf16 v[0:3], v[8:11], v[238:241], v[0:3]
	v_mfma_f32_16x16x32_bf16 v[4:7], v[206:209], v[238:241], v[4:7]
	v_mfma_f32_16x16x32_bf16 v[56:59], v[202:205], v[28:31], v[16:19]
	v_mfma_f32_16x16x32_bf16 v[48:51], v[210:213], v[28:31], v[24:27]
	v_mfma_f32_16x16x32_bf16 v[40:43], v[202:205], v[214:217], v[32:35]
	v_mfma_f32_16x16x32_bf16 v[32:35], v[210:213], v[214:217], v[142:145]
	v_mfma_f32_16x16x32_bf16 v[24:27], v[202:205], v[226:229], v[158:161]
	v_mfma_f32_16x16x32_bf16 v[16:19], v[210:213], v[226:229], v[162:165]
	v_mfma_f32_16x16x32_bf16 v[8:11], v[202:205], v[242:245], v[0:3]
	v_mfma_f32_16x16x32_bf16 v[0:3], v[210:213], v[242:245], v[4:7]
	s_barrier
	s_add_u32 s34, s28, 0x40180
	s_addc_u32 s35, s29, 0
	s_mov_b32 m0, s59
	v_lshl_add_u64 v[4:5], s[34:35], 0, v[134:135]
	s_add_i32 s17, s59, 0x2000
	global_load_lds_dwordx4 v[4:5], off
	v_lshl_add_u64 v[4:5], s[34:35], 0, v[130:131]
	s_mov_b32 m0, s17
	s_mov_b64 s[34:35], 0x40180
	global_load_lds_dwordx4 v[4:5], off
	s_waitcnt vmcnt(6)
	s_barrier
	v_mfma_f32_16x16x32_bf16 v[4:7], v[52:55], v[20:23], v[182:185]
	v_mfma_f32_16x16x32_bf16 v[12:15], v[68:71], v[20:23], v[12:15]
	v_mfma_f32_16x16x32_bf16 v[20:23], v[52:55], v[36:39], v[44:47]
	v_mfma_f32_16x16x32_bf16 v[36:39], v[68:71], v[36:39], v[186:189]
	v_mfma_f32_16x16x32_bf16 v[142:145], v[52:55], v[222:225], v[178:181]
	v_mfma_f32_16x16x32_bf16 v[158:161], v[68:71], v[222:225], v[190:193]
	v_mfma_f32_16x16x32_bf16 v[162:165], v[52:55], v[238:241], v[194:197]
	v_mfma_f32_16x16x32_bf16 v[166:169], v[68:71], v[238:241], v[198:201]
	v_mfma_f32_16x16x32_bf16 v[68:71], v[230:233], v[28:31], v[4:7]
	v_mfma_f32_16x16x32_bf16 v[52:55], v[234:237], v[28:31], v[12:15]
	v_mfma_f32_16x16x32_bf16 v[44:47], v[230:233], v[214:217], v[20:23]
	v_mfma_f32_16x16x32_bf16 v[36:39], v[234:237], v[214:217], v[36:39]
	v_mfma_f32_16x16x32_bf16 v[28:31], v[230:233], v[226:229], v[142:145]
	v_mfma_f32_16x16x32_bf16 v[20:23], v[234:237], v[226:229], v[158:161]
	v_mfma_f32_16x16x32_bf16 v[12:15], v[230:233], v[242:245], v[162:165]
	v_mfma_f32_16x16x32_bf16 v[4:7], v[234:237], v[242:245], v[166:169]
	v_lshl_add_u64 v[142:143], s[26:27], 0, v[138:139]
	v_lshl_add_u64 v[144:145], s[26:27], 0, v[140:141]
	s_mov_b32 s19, 0
